# attention: per-tile barrier right after the 3rd P.V MFMA of sub-step 1 (five-MFMA head, all softmax VALU ahead of it)
# baseline (speedup 1.0000x reference)
; __device__ __forceinline__ unsigned pk2(float lo, float hi) { return pg8::cvt_pk_bf16(lo, hi); }
; #define MFMA32(a, b, c) __builtin_amdgcn_mfma_f32_32x32x16_bf16((a), (b), (c), 0, 0, 0)
; __device__ __forceinline__ void attn_phase(const Args& a, int l, bool with_ctx, unsigned char* lds) {
;     ...
;                 for (int r = 0; r < 16; ++r) { S[r] = __builtin_amdgcn_exp2f(S[r]); ps += S[r]; }
;                 lrun += ps;
;                 u32x4 p0, p1;
;                 p0.x = pk2(S[0], S[1]); p0.y = pk2(S[2], S[3]); p0.z = pk2(S[4], S[5]); p0.w = pk2(S[6], S[7]);
;                 p1.x = pk2(S[8], S[9]); p1.y = pk2(S[10], S[11]); p1.z = pk2(S[12], S[13]); p1.w = pk2(S[14], S[15]);
;                 const bf16x8 pa0 = __builtin_bit_cast(bf16x8, p0), pa1 = __builtin_bit_cast(bf16x8, p1);
; #pragma unroll
;                 for (int j = 0; j < 4; ++j) O[j] = MFMA32(vf[2 * j], pa0, O[j]);
; #pragma unroll
;                 for (int j = 0; j < 4; ++j) O[j] = MFMA32(vf[2 * j + 1], pa1, O[j]);
;             }
;             if (t + 1 < nt) { unsigned char* kd = kdst + (cur ^ 1) * BUF; unsigned char* vd = vdst + (cur ^ 1) * BUF;
;                 *(u32x4*)kd = k0; *(u32x4*)(kd + 9216) = k1; *(u32x4*)vd = v0; *(u32x4*)(vd + 9216) = v1; }
;             __syncthreads();
.LBB0_412:
	v_exp_f32_e32 v67, v68
	v_exp_f32_e32 v68, v69
	v_exp_f32_e32 v69, v70
	v_exp_f32_e32 v70, v71
	v_exp_f32_e32 v71, v72
	v_exp_f32_e32 v72, v73
	v_exp_f32_e32 v73, v74
	v_exp_f32_e32 v74, v75
	v_cvt_pk_bf16_f32 v184, v67, v68
	v_cvt_pk_bf16_f32 v185, v69, v70
	v_cvt_pk_bf16_f32 v186, v71, v72
	v_cvt_pk_bf16_f32 v187, v73, v74
	v_exp_f32_e32 v75, v76
	v_exp_f32_e32 v76, v77
	s_waitcnt lgkmcnt(11)
	v_mfma_f32_32x32x16_bf16 v[50:65], v[136:139], v[184:187], v[50:65]
	v_exp_f32_e32 v77, v78
	v_exp_f32_e32 v78, v79
	v_exp_f32_e32 v79, v80
	v_exp_f32_e32 v80, v81
	v_exp_f32_e32 v81, v82
	v_exp_f32_e32 v82, v83
	v_cvt_pk_bf16_f32 v214, v75, v76
	s_waitcnt lgkmcnt(9)
	v_mfma_f32_32x32x16_bf16 v[34:49], v[140:143], v[184:187], v[34:49]
	v_cvt_pk_bf16_f32 v215, v77, v78
	v_cvt_pk_bf16_f32 v216, v79, v80
	v_cvt_pk_bf16_f32 v217, v81, v82
	s_andn2_b64 vcc, exec, s[10:11]
	s_waitcnt lgkmcnt(7)
	v_mfma_f32_32x32x16_bf16 v[18:33], v[144:147], v[184:187], v[18:33]
	s_waitcnt lgkmcnt(0)
	s_barrier
	s_waitcnt lgkmcnt(5)
	v_mfma_f32_32x32x16_bf16 v[2:17], v[132:135], v[184:187], v[2:17]
	v_mfma_f32_32x32x16_bf16 v[50:65], v[116:119], v[214:217], v[50:65]
	v_mfma_f32_32x32x16_bf16 v[34:49], v[120:123], v[214:217], v[34:49]
	v_mfma_f32_32x32x16_bf16 v[18:33], v[124:127], v[214:217], v[18:33]
	s_waitcnt lgkmcnt(4)
	v_mfma_f32_32x32x16_bf16 v[2:17], v[128:131], v[214:217], v[2:17]
